# build_tables f64 loop: the five per-index loads issued together at the loop top (counted waits) instead of four serial round trips
# baseline (speedup 1.0000x reference)
.LBB0_340:
	s_or_b64 exec, exec, s[60:61]
	v_add_f64 v[52:53], v[52:53], -1.0
	v_mul_f64 v[50:51], v[48:49], v[48:49]
	v_mul_f64 v[58:59], v[52:53], v[54:55]
	v_fmac_f64_e32 v[50:51], v[54:55], v[54:55]
	v_fmac_f64_e32 v[58:59], v[46:47], v[48:49]
	v_div_scale_f64 v[60:61], s[60:61], v[50:51], v[50:51], v[58:59]
	v_rcp_f64_e32 v[62:63], v[60:61]
	v_mul_f64 v[48:49], v[52:53], v[48:49]
	v_fma_f64 v[46:47], v[46:47], v[54:55], -v[48:49]
	v_div_scale_f64 v[48:49], s[60:61], v[50:51], v[50:51], v[46:47]
	v_rcp_f64_e32 v[52:53], v[48:49]
	v_fma_f64 v[64:65], -v[60:61], v[62:63], 1.0
	v_fmac_f64_e32 v[62:63], v[62:63], v[64:65]
	v_fma_f64 v[64:65], -v[60:61], v[62:63], 1.0
	v_fmac_f64_e32 v[62:63], v[62:63], v[64:65]
	v_div_scale_f64 v[64:65], vcc, v[58:59], v[50:51], v[58:59]
	v_fma_f64 v[54:55], -v[48:49], v[52:53], 1.0
	v_mul_f64 v[66:67], v[64:65], v[62:63]
	v_fmac_f64_e32 v[52:53], v[52:53], v[54:55]
	v_fma_f64 v[60:61], -v[60:61], v[66:67], v[64:65]
	v_fma_f64 v[54:55], -v[48:49], v[52:53], 1.0
	v_div_fmas_f64 v[60:61], v[60:61], v[62:63], v[66:67]
	v_fmac_f64_e32 v[52:53], v[52:53], v[54:55]
	v_div_scale_f64 v[54:55], vcc, v[46:47], v[50:51], v[46:47]
	v_div_fixup_f64 v[58:59], v[60:61], v[50:51], v[58:59]
	v_mul_f64 v[60:61], v[54:55], v[52:53]
	v_fma_f64 v[48:49], -v[48:49], v[60:61], v[54:55]
	s_nop 0
	v_div_fmas_f64 v[48:49], v[48:49], v[52:53], v[60:61]
	v_div_fixup_f64 v[46:47], v[48:49], v[50:51], v[46:47]
	v_lshlrev_b64 v[42:43], 12, v[42:43]
	v_lshl_add_u64 v[42:43], s[76:77], 0, v[42:43]
	v_add_u32_e32 v56, s8, v56
	v_cmp_lt_i32_e32 vcc, s3, v56
	v_lshl_add_u64 v[40:41], v[40:41], 0, s[20:21]
	s_or_b64 s[22:23], vcc, s[22:23]
	s_waitcnt vmcnt(0)
	v_cvt_f64_f32_e32 v[48:49], v76
	v_cvt_f64_f32_e32 v[50:51], v77
	v_mul_f64 v[52:53], v[46:47], v[50:51]
	v_mul_f64 v[50:51], v[58:59], v[50:51]
	v_fma_f64 v[52:53], v[58:59], v[48:49], -v[52:53]
	v_fmac_f64_e32 v[50:51], v[46:47], v[48:49]
	v_cvt_f32_f64_e32 v10, v[52:53]
	v_cvt_f32_f64_e32 v18, v[50:51]
	v_cvt_pk_bf16_f32 v10, v10, v18
	v_lshlrev_b32_e32 v18, 6, v44
	v_and_b32_e32 v34, 0xfc0, v18
	v_lshl_add_u64 v[42:43], v[42:43], 0, v[34:35]
	v_lshlrev_b32_e32 v34, 1, v210
	v_lshl_add_u64 v[42:43], v[42:43], 0, v[34:35]
	global_store_short v[42:43], v10, off
	global_store_short_d16_hi v[42:43], v10, off offset:32
	s_andn2_b64 exec, exec, s[22:23]
	s_cbranch_execz .LBB0_349
.LBB0_341:
	v_ashrrev_i32_e32 v42, 10, v56
	v_ashrrev_i32_e32 v43, 31, v42
	v_lshl_add_u64 v[46:47], v[42:43], 2, s[42:43]
	global_load_dword v10, v[46:47], off
	v_ashrrev_i32_e32 v44, 4, v56
	v_ashrrev_i32_e32 v45, 31, v44
	v_lshlrev_b64 v[70:71], 2, v[44:45]
	v_lshl_add_u64 v[72:73], s[40:41], 0, v[70:71]
	v_lshl_add_u64 v[70:71], s[38:39], 0, v[70:71]
	global_load_dword v74, v[72:73], off
	global_load_dword v75, v[70:71], off
	v_lshl_add_u64 v[70:71], s[44:45], 0, v[40:41]
	v_lshl_add_u64 v[72:73], s[46:47], 0, v[40:41]
	global_load_dword v76, v[70:71], off
	global_load_dword v77, v[72:73], off
	s_waitcnt vmcnt(4)
	v_cvt_f64_f32_e32 v[46:47], v10
	v_mul_f64 v[48:49], v[46:47], s[62:63]
	v_rndne_f64_e32 v[48:49], v[48:49]
	v_fmac_f64_e32 v[46:47], s[66:67], v[48:49]
	v_fmac_f64_e32 v[46:47], s[70:71], v[48:49]
	v_fma_f64 v[50:51], s[82:83], v[46:47], v[4:5]
	v_fma_f64 v[50:51], v[46:47], v[50:51], v[6:7]
	v_fma_f64 v[50:51], v[46:47], v[50:51], s[84:85]
	v_fma_f64 v[50:51], v[46:47], v[50:51], s[86:87]
	v_fma_f64 v[50:51], v[46:47], v[50:51], v[12:13]
	v_fma_f64 v[50:51], v[46:47], v[50:51], v[14:15]
	v_fma_f64 v[50:51], v[46:47], v[50:51], s[88:89]
	v_fma_f64 v[50:51], v[46:47], v[50:51], s[10:11]
	v_fma_f64 v[50:51], v[46:47], v[50:51], v[20:21]
	v_fma_f64 v[50:51], v[46:47], v[50:51], 0.5
	v_fma_f64 v[50:51], v[46:47], v[50:51], 1.0
	v_cvt_i32_f64_e32 v10, v[48:49]
	v_lshlrev_b64 v[48:49], 2, v[44:45]
	v_fma_f64 v[46:47], v[46:47], v[50:51], 1.0
	v_lshl_add_u64 v[50:51], s[38:39], 0, v[48:49]
	v_lshl_add_u64 v[48:49], s[40:41], 0, v[48:49]
	v_ldexp_f64 v[46:47], v[46:47], v10
	s_waitcnt vmcnt(2)
	v_cvt_f64_f32_e32 v[48:49], v74
	v_mul_f64 v[50:51], v[46:47], v[48:49]
	v_mul_f64 v[52:53], v[50:51], s[28:29]
	v_rndne_f64_e32 v[52:53], v[52:53]
	v_fmac_f64_e32 v[50:51], s[80:81], v[52:53]
	v_fmac_f64_e32 v[50:51], s[90:91], v[52:53]
	v_cvt_i32_f64_e32 v18, v[52:53]
	v_mul_f64 v[52:53], v[50:51], v[50:51]
	v_fma_f64 v[54:55], s[68:69], v[52:53], v[22:23]
	v_fma_f64 v[54:55], v[52:53], v[54:55], s[84:85]
	v_fma_f64 v[54:55], v[52:53], v[54:55], v[24:25]
	v_fma_f64 v[54:55], v[52:53], v[54:55], s[88:89]
	v_fma_f64 v[54:55], v[52:53], v[54:55], v[26:27]
	v_fma_f64 v[54:55], v[52:53], v[54:55], 1.0
	v_mul_f64 v[50:51], v[50:51], v[54:55]
	v_fma_f64 v[54:55], s[34:35], v[52:53], v[28:29]
	v_fma_f64 v[54:55], v[52:53], v[54:55], v[30:31]
	v_fma_f64 v[54:55], v[52:53], v[54:55], s[86:87]
	v_fma_f64 v[54:55], v[52:53], v[54:55], v[32:33]
	v_fma_f64 v[54:55], v[52:53], v[54:55], s[10:11]
	v_fma_f64 v[54:55], v[52:53], v[54:55], -0.5
	v_and_b32_e32 v18, 3, v18
	v_fma_f64 v[52:53], v[52:53], v[54:55], 1.0
	v_cmp_lt_i32_e32 vcc, 0, v18
	s_and_saveexec_b64 s[60:61], vcc
	s_cbranch_execz .LBB0_347
	v_cmp_ne_u32_e32 vcc, 1, v18
	v_xor_b32_e32 v55, 0x80000000, v51
	v_mov_b32_e32 v54, v50
	s_and_saveexec_b64 s[64:65], vcc
	s_xor_b64 s[64:65], exec, s[64:65]
	v_cmp_eq_u32_e32 vcc, 2, v18
	v_xor_b32_e32 v18, 0x80000000, v53
	s_nop 0
	v_cndmask_b32_e32 v58, v52, v50, vcc
	v_cndmask_b32_e64 v59, -v53, -v51, vcc
	v_cndmask_b32_e32 v55, v51, v18, vcc
	v_cndmask_b32_e32 v54, v50, v52, vcc
	v_mov_b64_e32 v[50:51], v[58:59]
	s_andn2_saveexec_b64 s[64:65], s[64:65]
	v_mov_b64_e32 v[50:51], v[52:53]
	s_or_b64 exec, exec, s[64:65]
	v_mov_b64_e32 v[52:53], v[54:55]
.LBB0_347:
	s_or_b64 exec, exec, s[60:61]
	v_cvt_f64_f32_e32 v[54:55], v75
	v_mul_f64 v[46:47], v[46:47], v[54:55]
	v_mul_f64 v[58:59], v[46:47], s[62:63]
	v_rndne_f64_e32 v[58:59], v[58:59]
	v_fmac_f64_e32 v[46:47], s[66:67], v[58:59]
	v_fmac_f64_e32 v[46:47], s[70:71], v[58:59]
	v_mov_b64_e32 v[60:61], v[4:5]
	v_fmac_f64_e32 v[60:61], s[82:83], v[46:47]
	v_mov_b64_e32 v[62:63], v[6:7]
	v_fmac_f64_e32 v[62:63], v[46:47], v[60:61]
	v_mov_b64_e32 v[60:61], v[36:37]
	v_fmac_f64_e32 v[60:61], v[46:47], v[62:63]
	v_mov_b64_e32 v[62:63], v[8:9]
	v_mov_b32_e32 v10, v8
	v_fmac_f64_e32 v[62:63], v[46:47], v[60:61]
	v_mov_b64_e32 v[60:61], v[10:11]
	v_fmac_f64_e32 v[60:61], v[46:47], v[62:63]
	v_mov_b64_e32 v[62:63], v[14:15]
	v_fmac_f64_e32 v[62:63], v[46:47], v[60:61]
	v_mov_b64_e32 v[60:61], v[38:39]
	v_fmac_f64_e32 v[60:61], v[46:47], v[62:63]
	v_mov_b64_e32 v[62:63], v[16:17]
	v_mov_b32_e32 v18, v16
	v_fmac_f64_e32 v[62:63], v[46:47], v[60:61]
	v_mov_b64_e32 v[60:61], v[18:19]
	v_fmac_f64_e32 v[60:61], v[46:47], v[62:63]
	v_fma_f64 v[60:61], v[46:47], v[60:61], 0.5
	v_fma_f64 v[60:61], v[46:47], v[60:61], 1.0
	v_fma_f64 v[46:47], v[46:47], v[60:61], 1.0
	v_cvt_i32_f64_e32 v10, v[58:59]
	v_ldexp_f64 v[46:47], v[46:47], v10
	v_mul_f64 v[52:53], v[46:47], v[52:53]
	v_mul_f64 v[46:47], v[46:47], v[50:51]
	s_and_saveexec_b64 s[60:61], s[96:97]
	s_cbranch_execz .LBB0_340
	v_lshlrev_b32_e32 v58, 1, v44
	v_readlane_b32 s4, v254, 20
	v_ashrrev_i32_e32 v59, 31, v58
	v_readlane_b32 s5, v254, 21
	v_cvt_f32_f64_e32 v50, v[52:53]
	v_cvt_f32_f64_e32 v51, v[46:47]
	v_lshl_add_u64 v[58:59], v[58:59], 2, s[4:5]
	global_store_dwordx2 v[58:59], v[50:51], off
	s_branch .LBB0_340
